# attention: V rows coalesced + LDS relayout, V prefetch moved to the start of q-tile 1, no waits between a wave's relayout LDS writes and reads
# speedup vs baseline: 1.0155x; 1.0013x over previous
.LBB0_341:
	s_or_b64 exec, exec, s[2:3]
	v_and_b32_e32 v183, 0x1fe, v182
	v_add_u32_e32 v0, s7, v183
	v_cmp_gt_i32_e32 vcc, 0, v0
	s_and_saveexec_b64 s[2:3], vcc
	s_xor_b64 s[2:3], exec, s[2:3]
	v_lshlrev_b32_e32 v0, 2, v251
	v_and_b32_e32 v120, 12, v0
	v_mov_b32_e32 v121, 0
	s_or_saveexec_b64 s[2:3], s[2:3]
	v_mov_b32_e32 v97, 0
	v_mov_b32_e32 v122, 0
	v_mov_b32_e32 v123, 0
	v_mov_b32_e32 v132, 0
	v_mov_b32_e32 v133, 0
	v_mov_b32_e32 v124, 0
	v_mov_b32_e32 v125, 0
	v_mov_b32_e32 v136, 0
	v_mov_b32_e32 v137, 0
	v_mov_b32_e32 v128, 0
	v_mov_b32_e32 v129, 0
	v_mov_b32_e32 v138, 0
	v_mov_b32_e32 v139, 0
	v_mov_b32_e32 v130, 0
	v_mov_b32_e32 v131, 0
	v_mov_b32_e32 v134, 0
	v_mov_b32_e32 v135, 0
	s_xor_b64 exec, exec, s[2:3]
	s_cbranch_execz .LBB0_345
	v_add_u32_e32 v2, s7, v250
	v_lshl_add_u32 v2, s6, 11, v2
	v_readlane_b32 s6, v255, 6
	v_readlane_b32 s7, v255, 7
	s_movk_i32 s4, 0xc00
	v_mov_b32_e32 v121, 0
	v_mov_b64_e32 v[0:1], s[6:7]
	v_mad_i64_i32 v[0:1], s[4:5], v2, s4, v[0:1]
	v_lshlrev_b32_e32 v2, 2, v251
	s_lshl_b32 s4, s1, 7
	s_mov_b32 s5, 0
	v_and_b32_e32 v120, 12, v2
	v_lshl_add_u64 v[0:1], v[0:1], 0, s[4:5]
	v_lshl_add_u64 v[0:1], v[0:1], 0, v[248:249]
	s_movk_i32 s4, 0x6000
	global_load_dwordx4 v[122:125], v[0:1], off offset:2560
	v_lshl_add_u64 v[0:1], v[0:1], 0, s[4:5]
	global_load_dwordx4 v[128:131], v[0:1], off offset:2560
	v_lshl_add_u64 v[0:1], v[0:1], 0, s[4:5]
	global_load_dwordx4 v[132:135], v[0:1], off offset:2560
	v_lshl_add_u64 v[0:1], v[0:1], 0, s[4:5]
	global_load_dwordx4 v[136:139], v[0:1], off offset:2560
.LBB0_345:
	s_or_b64 exec, exec, s[2:3]
	v_mbcnt_lo_u32_b32 v0, -1, 0
	v_mbcnt_hi_u32_b32 v4, -1, v0
	v_and_b32_e32 v1, 64, v4
	v_xor_b32_e32 v0, 1, v4
	v_add_u32_e32 v5, 64, v1
	v_bfe_u32 v3, v251, 5, 1
	v_cmp_lt_i32_e32 vcc, v0, v5
	v_xor_b32_e32 v10, 32, v4
	v_and_b32_e32 v184, 31, v251
	v_cndmask_b32_e32 v0, v4, v0, vcc
	v_cmp_lt_i32_e32 vcc, v10, v5
	v_lshlrev_b32_e32 v5, 2, v3
	v_or_b32_e32 v16, 2, v5
	v_cmp_gt_u32_e64 s[6:7], v16, v184
	v_or_b32_e32 v16, 3, v5
	s_add_u32 s82, s84, 0x80000
	v_cmp_gt_u32_e64 s[8:9], v16, v184
	v_or_b32_e32 v16, 8, v5
	s_addc_u32 s83, s85, 0
	v_cmp_gt_u32_e64 s[10:11], v16, v184
	v_or_b32_e32 v16, 9, v5
	s_add_u32 s92, s84, 0xc0000
	v_cmp_gt_u32_e64 s[12:13], v16, v184
	v_or_b32_e32 v16, 10, v5
	s_addc_u32 s93, s85, 0
	s_lshr_b32 s1, s0, 7
	s_and_b32 s91, s0, 64
	s_movk_i32 s0, 0x90
	v_cmp_gt_u32_e64 s[14:15], v16, v184
	v_or_b32_e32 v16, 11, v5
	v_mad_u32_u24 v6, v182, s0, 0
	s_movk_i32 s0, 0x208
	v_cmp_gt_u32_e64 s[16:17], v16, v184
	v_or_b32_e32 v16, 16, v5
	v_lshlrev_b32_e32 v96, 4, v3
	v_mad_u32_u24 v9, v120, s0, 0
	v_cndmask_b32_e32 v4, v4, v10, vcc
	s_lshr_b32 s0, s91, 5
	v_cmp_gt_u32_e64 s[18:19], v16, v184
	v_or_b32_e32 v16, 17, v5
	v_writelane_b32 v255, s1, 14
	v_lshlrev_b32_e32 v126, 3, v3
	v_lshlrev_b32_e32 v188, 2, v4
	v_add_u32_e32 v4, 0, v96
	s_or_b32 s1, s0, 1
	s_add_i32 s33, s0, 2
	s_add_i32 s54, s0, 3
	s_or_b32 s0, s0, 4
	v_cmp_gt_u32_e64 s[20:21], v16, v184
	v_or_b32_e32 v16, 18, v5
	v_sub_u32_e32 v10, v4, v126
	v_cmp_gt_u32_e64 s[22:23], v16, v184
	v_or_b32_e32 v16, 19, v5
	s_cmp_eq_u32 s91, 0
	v_readlane_b32 s2, v255, 6
	v_lshl_or_b32 v15, s0, 5, v184
	v_cmp_gt_u32_e64 s[24:25], v16, v184
	v_or_b32_e32 v16, 24, v5
	s_cselect_b64 s[36:37], -1, 0
	v_lshl_add_u32 v20, s0, 6, v10
	s_or_b32 s0, s91, 32
	v_mov_b32_e32 v127, v97
	v_readlane_b32 s3, v255, 7
	v_lshl_or_b32 v12, s1, 5, v184
	v_cmp_gt_u32_e64 s[26:27], v16, v184
	v_or_b32_e32 v16, 25, v5
	v_lshl_add_u32 v17, s1, 6, v10
	s_lshr_b32 s1, s0, 5
	v_lshl_add_u64 v[146:147], s[2:3], 0, v[126:127]
	v_lshl_or_b32 v13, s33, 5, v184
	v_lshl_or_b32 v14, s54, 5, v184
	v_cmp_gt_u32_e64 s[2:3], v5, v184
	v_cmp_lt_u32_e64 s[4:5], v5, v184
	v_cmp_gt_u32_e64 s[28:29], v16, v184
	v_or_b32_e32 v16, 26, v5
	v_or_b32_e32 v5, 27, v5
	v_lshl_add_u32 v18, s33, 6, v10
	v_lshl_add_u32 v19, s54, 6, v10
	s_add_i32 s33, s1, 1
	s_add_i32 s54, s1, 2
	s_add_i32 s55, s1, 3
	s_or_b32 s1, s1, 4
	v_writelane_b32 v255, s0, 15
	v_and_b32_e32 v2, 1, v251
	v_cmp_gt_u32_e64 s[34:35], v5, v184
	v_lshl_add_u32 v5, s91, 1, v10
	v_or_b32_e32 v21, s0, v184
	v_lshl_or_b32 v25, s1, 5, v184
	v_lshl_add_u32 v26, s0, 1, v10
	v_lshl_add_u32 v27, s33, 6, v10
	v_lshl_add_u32 v28, s54, 6, v10
	v_lshl_add_u32 v29, s55, 6, v10
	v_lshl_add_u32 v10, s1, 6, v10
	v_readlane_b32 s0, v255, 1
	v_or_b32_e32 v185, s91, v184
	v_lshlrev_b32_e32 v187, 2, v0
	v_lshlrev_b32_e32 v0, 6, v2
	v_lshlrev_b32_e32 v7, 5, v2
	v_lshlrev_b32_e32 v2, 4, v251
	v_lshl_or_b32 v22, s33, 5, v184
	v_lshl_or_b32 v23, s54, 5, v184
	v_lshl_or_b32 v24, s55, 5, v184
	v_readlane_b32 s1, v255, 2
	v_mov_b32_e32 v1, v97
	v_and_b32_e32 v8, 0x3fc, v251
	v_and_b32_e32 v2, 16, v2
	v_mul_u32_u24_e32 v11, 0x90, v185
	v_mul_u32_u24_e32 v12, 0x90, v12
	v_mul_u32_u24_e32 v13, 0x90, v13
	v_mul_u32_u24_e32 v14, 0x90, v14
	v_mul_u32_u24_e32 v15, 0x90, v15
	v_cmp_gt_u32_e64 s[30:31], v16, v184
	v_mul_u32_u24_e32 v16, 0x208, v184
	v_mul_u32_u24_e32 v21, 0x90, v21
	v_mul_u32_u24_e32 v22, 0x90, v22
	v_mul_u32_u24_e32 v23, 0x90, v23
	v_mul_u32_u24_e32 v24, 0x90, v24
	v_mul_u32_u24_e32 v25, 0x90, v25
	v_lshlrev_b32_e32 v96, 5, v3
	s_lshl_b32 s1, s0, 5
	s_lshl_b32 s0, s0, 2
	v_add_u32_e32 v186, 0xffffff80, v182
	s_mov_b32 s95, 0
	v_lshl_add_u64 v[142:143], s[82:83], 0, v[0:1]
	v_lshl_add_u64 v[144:145], s[92:93], 0, v[0:1]
	v_or_b32_e32 v127, 16, v126
	v_lshl_add_u64 v[148:149], s[78:79], 0, v[0:1]
	v_lshl_add_u64 v[150:151], s[76:77], 0, v[96:97]
	v_mov_b32_e32 v242, 0
	v_add_u32_e32 v242, 0x1b000, v242
	v_add_u32_e32 v243, v242, v96
	v_add_u32_e32 v243, 0x100, v243
	v_add_u32_e32 v242, v242, v0
	s_lshl_b32 s90, s97, 2
	v_writelane_b32 v255, s0, 16
	s_movk_i32 s65, 0xc00
	s_mov_b32 s54, 0xffff0000
	v_mov_b32_e32 v189, 0x358637bd
	v_add_u32_e32 v190, v6, v7
	v_add_u32_e32 v191, v9, v8
	v_lshlrev_b32_e32 v152, 1, v2
	v_add_u32_e32 v192, v4, v11
	v_add_u32_e32 v193, v4, v12
	v_add_u32_e32 v194, v4, v13
	v_add_u32_e32 v195, v4, v14
	v_add_u32_e32 v196, v4, v15
	v_add_u32_e32 v197, v5, v16
	v_add_u32_e32 v198, v17, v16
	v_add_u32_e32 v199, v18, v16
	v_add_u32_e32 v200, v19, v16
	v_add_u32_e32 v201, v20, v16
	v_add_u32_e32 v202, v4, v21
	v_add_u32_e32 v203, v4, v22
	v_add_u32_e32 v204, v4, v23
	v_add_u32_e32 v205, v4, v24
	v_add_u32_e32 v206, v4, v25
	v_add_u32_e32 v207, v26, v16
	v_add_u32_e32 v208, v27, v16
	v_add_u32_e32 v209, v28, v16
	v_add_u32_e32 v210, v29, v16
	v_add_u32_e32 v211, v10, v16
	v_mov_b32_e32 v212, 0xff800000
	s_mov_b32 s33, s97
	s_branch .LBB0_348

.LBB0_348:
	ds_read_b128 v[24:27], v242 offset:16
	ds_read_b128 v[28:31], v242 offset:144
	s_bfe_u32 s88, s33, 0x40002
	s_lshl_b32 s68, s88, 7
	v_add_u32_e32 v0, s68, v186
	v_max_i32_e32 v0, 0, v0
	v_lshlrev_b32_e32 v96, 7, v0
	v_lshl_add_u64 v[48:49], v[142:143], 0, v[96:97]
	v_lshl_add_u64 v[98:99], v[144:145], 0, v[96:97]
	s_add_i32 s58, s68, 0xffffff80
	v_add_u32_e32 v230, s58, v250
	v_lshl_add_u32 v230, v230, 7, v248
	v_max_i32_e32 v231, v248, v230
	global_load_dwordx4 v[116:119], v231, s[82:83]
	global_load_dwordx4 v[154:157], v231, s[92:93]
	v_add_u32_e32 v230, 0x400, v230
	v_max_i32_e32 v231, v248, v230
	global_load_dwordx4 v[44:47], v231, s[82:83]
	global_load_dwordx4 v[68:71], v231, s[92:93]
	v_add_u32_e32 v230, 0x400, v230
	v_max_i32_e32 v231, v248, v230
	global_load_dwordx4 v[158:161], v231, s[82:83]
	global_load_dwordx4 v[162:165], v231, s[92:93]
	v_add_u32_e32 v230, 0x400, v230
	v_max_i32_e32 v231, v248, v230
	global_load_dwordx4 v[40:43], v231, s[82:83]
	global_load_dwordx4 v[48:51], v231, s[92:93]
	ds_read_b128 v[72:75], v242
	ds_read_b128 v[16:19], v242 offset:48
	ds_read_b128 v[32:35], v242 offset:32
	ds_read_b128 v[20:23], v242 offset:176
	ds_read_b128 v[36:39], v242 offset:160
	ds_read_b128 v[76:79], v242 offset:128
	s_mov_b32 s0, s97
	s_and_b32 s97, s90, 12
	s_and_b32 s89, s96, 0xfffff800
	v_readlane_b32 s55, v255, 14
	s_waitcnt vmcnt(12)
	v_and_b32_e32 v224, 63, v251
	v_lshrrev_b32_e32 v225, 3, v224
	s_movk_i32 s58, 0x90
	v_mul_u32_u24_e32 v226, 0x1200, v254
	v_add_u32_e32 v226, 0x12000, v226
	v_and_b32_e32 v227, 7, v224
	v_lshlrev_b32_e32 v227, 4, v227
	v_mad_u32_u24 v227, v225, s58, v227
	v_add_u32_e32 v227, v227, v226
	v_lshrrev_b32_e32 v225, 1, v224
	v_and_b32_e32 v224, 1, v224
	v_lshlrev_b32_e32 v224, 5, v224
	v_mad_u32_u24 v224, v225, s58, v224
	v_add_u32_e32 v224, v224, v226
	ds_write_b128 v227, v[80:83]
	ds_write_b128 v227, v[84:87] offset:1152
	ds_write_b128 v227, v[88:91] offset:2304
	ds_write_b128 v227, v[92:95] offset:3456
	ds_read_b128 v[80:83], v224
	ds_read_b128 v[84:87], v224 offset:16
	ds_read_b128 v[92:95], v224 offset:64
	ds_read_b128 v[88:91], v224 offset:80
	s_waitcnt lgkmcnt(0)
	v_and_b32_e32 v64, 0xffff0000, v84
	v_lshlrev_b32_e32 v65, 16, v84
	v_and_b32_e32 v60, 0xffff0000, v85
	v_lshlrev_b32_e32 v61, 16, v85
	s_add_i32 s97, s97, s55
	v_or_b32_e32 v8, s89, v185
	v_and_b32_e32 v66, 0xffff0000, v88
	v_lshlrev_b32_e32 v67, 16, v88
	v_and_b32_e32 v62, 0xffff0000, v89
	v_lshlrev_b32_e32 v63, 16, v89
	v_pk_mul_f32 v[0:1], v[64:65], v[64:65]
	v_pk_mul_f32 v[2:3], v[60:61], v[60:61]
	v_or_b32_e32 v8, s68, v8
	s_lshl_b32 s94, s97, 7
	v_and_b32_e32 v56, 0xffff0000, v86
	v_lshlrev_b32_e32 v57, 16, v86
	v_and_b32_e32 v52, 0xffff0000, v87
	v_lshlrev_b32_e32 v53, 16, v87
	v_pk_fma_f32 v[214:215], v[66:67], v[66:67], v[0:1]
	v_pk_fma_f32 v[216:217], v[62:63], v[62:63], v[2:3]
	v_or_b32_e32 v2, 32, v8
	v_and_b32_e32 v58, 0xffff0000, v90
	v_lshlrev_b32_e32 v59, 16, v90
	v_and_b32_e32 v54, 0xffff0000, v91
	v_lshlrev_b32_e32 v55, 16, v91
	v_pk_mul_f32 v[4:5], v[56:57], v[56:57]
	v_pk_mul_f32 v[6:7], v[52:53], v[52:53]
	v_pk_fma_f32 v[218:219], v[58:59], v[58:59], v[4:5]
	v_pk_fma_f32 v[220:221], v[54:55], v[54:55], v[6:7]
	v_readlane_b32 s78, v255, 6
	v_readlane_b32 s79, v255, 7
	s_or_b32 s58, s89, s68
	s_or_b32 s58, s58, s91
	v_and_b32_e32 v231, 7, v250
	v_add_u32_e32 v231, s58, v231
	v_add_u32_e32 v230, s94, v248
	v_mad_u32_u24 v230, v231, s65, v230
	s_nop 0
	global_load_dwordx4 v[0:3], v230, s[78:79]
	v_add_u32_e32 v230, 0x6000, v230
	global_load_dwordx4 v[4:7], v230, s[78:79]
	v_add_u32_e32 v230, 0x6000, v230
	global_load_dwordx4 v[8:11], v230, s[78:79]
	v_add_u32_e32 v230, 0x6000, v230
	global_load_dwordx4 v[12:15], v230, s[78:79]
	v_add_u32_e32 v230, 0x6000, v230
	global_load_dwordx4 v[100:103], v230, s[78:79]
	v_add_u32_e32 v230, 0x6000, v230
	global_load_dwordx4 v[104:107], v230, s[78:79]
	v_add_u32_e32 v230, 0x6000, v230
	global_load_dwordx4 v[108:111], v230, s[78:79]
	v_add_u32_e32 v230, 0x6000, v230
	global_load_dwordx4 v[112:115], v230, s[78:79]
	v_lshlrev_b32_e32 v239, 16, v92
	v_lshlrev_b32_e32 v238, 16, v80
	v_and_b32_e32 v245, 0xffff0000, v92
	v_and_b32_e32 v244, 0xffff0000, v80
	v_lshlrev_b32_e32 v229, 16, v93
	v_lshlrev_b32_e32 v228, 16, v81
	v_pk_mul_f32 v[240:241], v[238:239], v[238:239]
	v_pk_mul_f32 v[246:247], v[244:245], v[244:245]
	v_pk_mul_f32 v[230:231], v[228:229], v[228:229]
	v_and_b32_e32 v235, 0xffff0000, v93
	v_and_b32_e32 v234, 0xffff0000, v81
	v_lshlrev_b32_e32 v171, 16, v94
	v_lshlrev_b32_e32 v170, 16, v82
	v_pk_mul_f32 v[236:237], v[234:235], v[234:235]
	v_and_b32_e32 v173, 0xffff0000, v94
	v_and_b32_e32 v172, 0xffff0000, v82
	v_pk_mul_f32 v[178:179], v[170:171], v[170:171]
	v_lshlrev_b32_e32 v167, 16, v95
	v_lshlrev_b32_e32 v166, 16, v83
	v_pk_mul_f32 v[180:181], v[172:173], v[172:173]
	v_and_b32_e32 v169, 0xffff0000, v95
	v_and_b32_e32 v168, 0xffff0000, v83
	v_pk_mul_f32 v[174:175], v[166:167], v[166:167]
	v_pk_mul_f32 v[176:177], v[168:169], v[168:169]
	v_readlane_b32 s76, v255, 1
	s_add_i32 s33, s33, s76
	v_readlane_b32 s77, v255, 2
	s_cmpk_gt_i32 s33, 0x3ff
	s_cselect_b64 s[76:77], -1, 0
	s_waitcnt lgkmcnt(0)
	v_mov_b32_e32 v98, v26
	s_waitcnt lgkmcnt(0)
	v_mov_b32_e32 v223, v28
	v_add_f32_e32 v26, v247, v246
	v_add_f32_e32 v28, v241, v240
	v_add_f32_e32 v26, v28, v26
	v_add_f32_e32 v28, v231, v230
	v_mov_b32_e32 v222, v24
	v_add_f32_e32 v24, v237, v236
	v_add_f32_e32 v26, v28, v26
	v_add_f32_e32 v24, v24, v26
	v_add_f32_e32 v26, v179, v178
	v_add_f32_e32 v24, v26, v24
	v_add_f32_e32 v26, v181, v180
	v_add_f32_e32 v24, v26, v24
	v_add_f32_e32 v26, v175, v174
	v_add_f32_e32 v24, v26, v24
	v_add_f32_e32 v26, v177, v176
	v_add_f32_e32 v24, v26, v24
	v_add_f32_e32 v24, v215, v24
	v_add_f32_e32 v24, v214, v24
	v_add_f32_e32 v24, v217, v24
	v_add_f32_e32 v24, v216, v24
	v_add_f32_e32 v24, v219, v24
	v_add_f32_e32 v24, v218, v24
	v_add_f32_e32 v24, v221, v24
	v_add_f32_e32 v24, v220, v24
	ds_bpermute_b32 v26, v187, v24
	s_waitcnt vmcnt(8)
	ds_write_b128 v227, v[116:119]
	ds_write_b128 v227, v[44:47] offset:1152
	ds_write_b128 v227, v[158:161] offset:2304
	ds_write_b128 v227, v[40:43] offset:3456
	v_and_b32_e32 v225, 63, v251
	v_lshrrev_b32_e32 v224, 1, v225
	v_and_b32_e32 v225, 1, v225
	v_lshlrev_b32_e32 v225, 6, v225
	v_mul_u32_u24_e32 v224, 0x90, v224
	v_add3_u32 v225, v224, v225, v226
	ds_read_b128 v[116:119], v225
	ds_read_b128 v[44:47], v225 offset:16
	ds_read_b128 v[158:161], v225 offset:32
	ds_read_b128 v[40:43], v225 offset:48
	ds_write_b128 v227, v[154:157]
	ds_write_b128 v227, v[68:71] offset:1152
	ds_write_b128 v227, v[162:165] offset:2304
	ds_write_b128 v227, v[48:51] offset:3456
	ds_read_b128 v[154:157], v225
	ds_read_b128 v[68:71], v225 offset:16
	ds_read_b128 v[162:165], v225 offset:32
	ds_read_b128 v[48:51], v225 offset:48
	s_waitcnt lgkmcnt(0)
	s_waitcnt lgkmcnt(0)
	v_mov_b32_e32 v176, v72
	s_waitcnt lgkmcnt(0)
	v_mov_b32_e32 v177, v76
	v_mov_b32_e32 v178, v116
	v_mov_b32_e32 v179, v154
	s_waitcnt lgkmcnt(0)
	v_add_f32_e32 v24, v24, v26
	v_fmamk_f32 v24, v24, 0x3c800000, v189
	v_rsq_f32_e32 v24, v24
	v_mov_b32_e32 v76, v73
	v_mov_b32_e32 v232, v74
	v_mov_b32_e32 v233, v78
	v_pk_mul_f32 v[180:181], v[24:25], v[238:239] op_sel_hi:[0,1]
	v_pk_mul_f32 v[176:177], v[176:177], v[180:181]
	v_mov_b32_e32 v174, v118
	v_pk_mul_f32 v[178:179], v[178:179], v[176:177]
	v_mov_b32_e32 v175, v156
	v_sub_f32_e32 v96, v178, v179
	v_mov_b32_e32 v178, v154
	v_mov_b32_e32 v179, v116
	v_pk_mul_f32 v[176:177], v[178:179], v[176:177]
	v_mov_b32_e32 v154, v117
	v_add_f32_e32 v153, v177, v176
	v_pk_mul_f32 v[176:177], v[24:25], v[244:245] op_sel_hi:[0,1]
	v_pk_mul_f32 v[72:73], v[76:77], v[176:177]
	v_mov_b32_e32 v116, v155
	v_pk_mul_f32 v[76:77], v[154:155], v[72:73]
	v_pk_mul_f32 v[72:73], v[116:117], v[72:73]
	v_sub_f32_e32 v154, v76, v77
	v_add_f32_e32 v116, v73, v72
	v_pk_mul_f32 v[72:73], v[24:25], v[228:229] op_sel_hi:[0,1]
	v_pk_mul_f32 v[72:73], v[232:233], v[72:73]
	v_mov_b32_e32 v78, v75
	v_pk_mul_f32 v[76:77], v[174:175], v[72:73]
	v_mov_b32_e32 v226, v44
	v_sub_f32_e32 v117, v76, v77
	v_mov_b32_e32 v76, v156
	v_mov_b32_e32 v77, v118
	v_pk_mul_f32 v[72:73], v[76:77], v[72:73]
	v_mov_b32_e32 v156, v119
	v_add_f32_e32 v76, v73, v72
	v_pk_mul_f32 v[72:73], v[24:25], v[234:235] op_sel_hi:[0,1]
	v_pk_mul_f32 v[72:73], v[78:79], v[72:73]
	v_mov_b32_e32 v118, v157
	v_pk_mul_f32 v[74:75], v[156:157], v[72:73]
	v_pk_mul_f32 v[72:73], v[118:119], v[72:73]
	v_mov_b32_e32 v227, v68
	v_add_f32_e32 v78, v73, v72
	v_pk_mul_f32 v[72:73], v[24:25], v[170:171] op_sel_hi:[0,1]
	v_pk_mul_f32 v[72:73], v[72:73], v[222:223]
	v_sub_f32_e32 v77, v74, v75
	v_pk_mul_f32 v[74:75], v[72:73], v[226:227]
	v_mov_b32_e32 v28, v25
	v_sub_f32_e32 v79, v74, v75
	v_mov_b32_e32 v74, v68
	v_mov_b32_e32 v75, v44
	v_pk_mul_f32 v[72:73], v[72:73], v[74:75]
	v_mov_b32_e32 v68, v45
	v_add_f32_e32 v74, v73, v72
	v_pk_mul_f32 v[72:73], v[24:25], v[172:173] op_sel_hi:[0,1]
	v_pk_mul_f32 v[28:29], v[72:73], v[28:29]
	v_mov_b32_e32 v44, v69
	v_pk_mul_f32 v[72:73], v[28:29], v[68:69]
	v_pk_mul_f32 v[28:29], v[28:29], v[44:45]
	v_sub_f32_e32 v25, v72, v73
	v_mov_b32_e32 v99, v30
	v_add_f32_e32 v68, v29, v28
	v_pk_mul_f32 v[28:29], v[24:25], v[166:167] op_sel_hi:[0,1]
	v_mov_b32_e32 v224, v46
	v_mov_b32_e32 v225, v70
	v_pk_mul_f32 v[28:29], v[28:29], v[98:99]
	v_mov_b32_e32 v30, v27
	v_pk_mul_f32 v[44:45], v[28:29], v[224:225]
	s_and_b64 vcc, exec, s[76:77]
	v_sub_f32_e32 v69, v44, v45
	v_mov_b32_e32 v44, v70
	v_mov_b32_e32 v45, v46
	v_pk_mul_f32 v[28:29], v[28:29], v[44:45]
	v_mov_b32_e32 v70, v47
	v_add_f32_e32 v44, v29, v28
	v_pk_mul_f32 v[28:29], v[24:25], v[168:169] op_sel_hi:[0,1]
	v_pk_mul_f32 v[26:27], v[28:29], v[30:31]
	v_mov_b32_e32 v46, v71
	v_pk_mul_f32 v[28:29], v[26:27], v[70:71]
	v_pk_mul_f32 v[26:27], v[26:27], v[46:47]
	v_sub_f32_e32 v30, v28, v29
	v_add_f32_e32 v31, v27, v26
	v_mov_b32_e32 v26, v65
	v_mov_b32_e32 v27, v67
	v_pk_mul_f32 v[26:27], v[24:25], v[26:27] op_sel_hi:[0,1]
	v_mov_b32_e32 v28, v32
	v_mov_b32_e32 v29, v36
	v_pk_mul_f32 v[26:27], v[26:27], v[28:29]
	v_mov_b32_e32 v28, v158
	v_mov_b32_e32 v29, v162
	v_pk_mul_f32 v[28:29], v[26:27], v[28:29]
	v_mov_b32_e32 v65, v66
	v_sub_f32_e32 v32, v28, v29
	v_mov_b32_e32 v28, v162
	v_mov_b32_e32 v29, v158
	v_pk_mul_f32 v[26:27], v[26:27], v[28:29]
	v_mov_b32_e32 v36, v33
	v_add_f32_e32 v45, v27, v26
	v_pk_mul_f32 v[26:27], v[24:25], v[64:65] op_sel_hi:[0,1]
	v_pk_mul_f32 v[26:27], v[26:27], v[36:37]
	v_mov_b32_e32 v162, v159
	v_mov_b32_e32 v158, v163
	v_pk_mul_f32 v[28:29], v[26:27], v[162:163]
	v_pk_mul_f32 v[26:27], v[26:27], v[158:159]
	v_sub_f32_e32 v33, v28, v29
	v_add_f32_e32 v36, v27, v26
	v_mov_b32_e32 v26, v61
	v_mov_b32_e32 v27, v63
	v_pk_mul_f32 v[26:27], v[24:25], v[26:27] op_sel_hi:[0,1]
	v_mov_b32_e32 v28, v34
	v_mov_b32_e32 v29, v38
	v_pk_mul_f32 v[26:27], v[26:27], v[28:29]
	v_mov_b32_e32 v28, v160
	v_mov_b32_e32 v29, v164
	v_pk_mul_f32 v[28:29], v[26:27], v[28:29]
	v_mov_b32_e32 v61, v62
	v_sub_f32_e32 v34, v28, v29
	v_mov_b32_e32 v28, v164
	v_mov_b32_e32 v29, v160
	v_pk_mul_f32 v[26:27], v[26:27], v[28:29]
	v_mov_b32_e32 v38, v35
	v_add_f32_e32 v37, v27, v26
	v_pk_mul_f32 v[26:27], v[24:25], v[60:61] op_sel_hi:[0,1]
	v_pk_mul_f32 v[26:27], v[26:27], v[38:39]
	v_mov_b32_e32 v164, v161
	v_mov_b32_e32 v160, v165
	v_pk_mul_f32 v[28:29], v[26:27], v[164:165]
	v_pk_mul_f32 v[26:27], v[26:27], v[160:161]
	v_sub_f32_e32 v35, v28, v29
	v_add_f32_e32 v38, v27, v26
	v_mov_b32_e32 v26, v57
	v_mov_b32_e32 v27, v59
	v_pk_mul_f32 v[26:27], v[24:25], v[26:27] op_sel_hi:[0,1]
	v_mov_b32_e32 v28, v16
	v_mov_b32_e32 v29, v20
	v_pk_mul_f32 v[26:27], v[26:27], v[28:29]
	v_mov_b32_e32 v28, v40
	v_mov_b32_e32 v29, v48
	v_pk_mul_f32 v[28:29], v[26:27], v[28:29]
	v_mov_b32_e32 v57, v58
	v_sub_f32_e32 v39, v28, v29
	v_mov_b32_e32 v28, v48
	v_mov_b32_e32 v29, v40
	v_pk_mul_f32 v[26:27], v[26:27], v[28:29]
	v_mov_b32_e32 v20, v17
	v_add_f32_e32 v28, v27, v26
	v_pk_mul_f32 v[26:27], v[24:25], v[56:57] op_sel_hi:[0,1]
	v_pk_mul_f32 v[16:17], v[26:27], v[20:21]
	v_mov_b32_e32 v48, v41
	v_mov_b32_e32 v40, v49
	v_pk_mul_f32 v[20:21], v[16:17], v[48:49]
	v_pk_mul_f32 v[16:17], v[16:17], v[40:41]
	v_sub_f32_e32 v26, v20, v21
	v_add_f32_e32 v27, v17, v16
	v_mov_b32_e32 v16, v53
	v_mov_b32_e32 v17, v55
	v_pk_mul_f32 v[16:17], v[24:25], v[16:17] op_sel_hi:[0,1]
	v_mov_b32_e32 v20, v18
	v_mov_b32_e32 v21, v22
	v_pk_mul_f32 v[16:17], v[16:17], v[20:21]
	v_mov_b32_e32 v20, v42
	v_mov_b32_e32 v21, v50
	v_pk_mul_f32 v[20:21], v[16:17], v[20:21]
	v_mov_b32_e32 v53, v54
	v_sub_f32_e32 v29, v20, v21
	v_mov_b32_e32 v20, v50
	v_mov_b32_e32 v21, v42
	v_pk_mul_f32 v[16:17], v[16:17], v[20:21]
	v_mov_b32_e32 v22, v19
	v_add_f32_e32 v20, v17, v16
	v_pk_mul_f32 v[16:17], v[24:25], v[52:53] op_sel_hi:[0,1]
	v_pk_mul_f32 v[16:17], v[16:17], v[22:23]
	v_mov_b32_e32 v50, v43
	v_mov_b32_e32 v42, v51
	v_pk_mul_f32 v[18:19], v[16:17], v[50:51]
	v_pk_mul_f32 v[16:17], v[16:17], v[42:43]
	v_sub_f32_e32 v21, v18, v19
	v_add_f32_e32 v22, v17, v16
	v_cvt_pk_bf16_f32 v16, v96, v154
	v_cvt_pk_bf16_f32 v17, v117, v77
	v_cvt_pk_bf16_f32 v18, v79, v25
	v_cvt_pk_bf16_f32 v19, v69, v30
	ds_write_b128 v190, v[16:19]
	v_cvt_pk_bf16_f32 v16, v32, v33
	v_cvt_pk_bf16_f32 v17, v34, v35
	v_cvt_pk_bf16_f32 v18, v39, v26
	v_cvt_pk_bf16_f32 v19, v29, v21
	ds_write_b128 v190, v[16:19] offset:16
	v_cvt_pk_bf16_f32 v16, v153, v116
	v_cvt_pk_bf16_f32 v17, v76, v78
	v_cvt_pk_bf16_f32 v18, v74, v68
	v_cvt_pk_bf16_f32 v19, v44, v31
	ds_write_b128 v190, v[16:19] offset:64
	v_cvt_pk_bf16_f32 v16, v45, v36
	v_cvt_pk_bf16_f32 v17, v37, v38
	v_cvt_pk_bf16_f32 v18, v28, v27
	v_cvt_pk_bf16_f32 v19, v20, v22
	ds_write_b128 v190, v[16:19] offset:80
	v_and_b32_e32 v20, 63, v251
	v_lshrrev_b32_e32 v21, 3, v20
	v_mul_u32_u24_e32 v21, 0x90, v21
	v_and_b32_e32 v22, 7, v20
	v_lshl_add_u32 v21, v22, 4, v21
	v_mul_u32_u24_e32 v22, 0x1200, v254
	v_add_u32_e32 v22, 0x12000, v22
	v_add_u32_e32 v21, v21, v22
	v_lshrrev_b32_e32 v23, 2, v20
	v_mul_u32_u24_e32 v23, 0x120, v23
	v_and_b32_e32 v20, 3, v20
	v_lshl_add_u32 v23, v20, 3, v23
	v_add_u32_e32 v23, v23, v22
	ds_write_b128 v21, v[122:125]
	ds_write_b128 v21, v[128:131] offset:1152
	ds_write_b128 v21, v[132:135] offset:2304
	ds_write_b128 v21, v[136:139] offset:3456
	ds_read_b64 v[122:123], v23
	ds_read_b64 v[124:125], v23 offset:32
	ds_read_b64 v[128:129], v23 offset:64
	ds_read_b64 v[130:131], v23 offset:96
	ds_read_b64 v[132:133], v23 offset:144
	ds_read_b64 v[136:137], v23 offset:176
	ds_read_b64 v[138:139], v23 offset:208
	ds_read_b64 v[140:141], v23 offset:240
	s_waitcnt lgkmcnt(0)
	v_and_b32_e32 v16, 0xffff, v122
	v_lshrrev_b32_e32 v17, 16, v122
	v_lshl_or_b32 v16, v132, 16, v16
	v_and_or_b32 v17, v132, s54, v17
	v_add_u32_e32 v18, 0x9000, v191
	ds_write2_b32 v18, v16, v17 offset1:130
	v_and_b32_e32 v16, 0xffff, v123
	v_lshrrev_b32_e32 v17, 16, v123
	v_lshl_or_b32 v16, v133, 16, v16
	v_and_or_b32 v17, v133, s54, v17
	v_add_u32_e32 v18, 0x9400, v191
	ds_write2_b32 v18, v16, v17 offset0:4 offset1:134
	v_and_b32_e32 v16, 0xffff, v124
	v_lshrrev_b32_e32 v17, 16, v124
	v_lshl_or_b32 v16, v136, 16, v16
	v_and_or_b32 v17, v136, s54, v17
	v_add_u32_e32 v18, 0xb000, v191
	ds_write2_b32 v18, v16, v17 offset0:32 offset1:162
	v_and_b32_e32 v16, 0xffff, v125
	v_lshrrev_b32_e32 v17, 16, v125
	v_lshl_or_b32 v16, v137, 16, v16
	v_and_or_b32 v17, v137, s54, v17
	v_add_u32_e32 v18, 0xb400, v191
	ds_write2_b32 v18, v16, v17 offset0:36 offset1:166
	v_and_b32_e32 v16, 0xffff, v128
	v_lshrrev_b32_e32 v17, 16, v128
	v_lshl_or_b32 v16, v138, 16, v16
	v_and_or_b32 v17, v138, s54, v17
	v_add_u32_e32 v18, 0xd000, v191
	ds_write2_b32 v18, v16, v17 offset0:64 offset1:194
	v_and_b32_e32 v16, 0xffff, v129
	v_lshrrev_b32_e32 v17, 16, v129
	v_lshl_or_b32 v16, v139, 16, v16
	v_and_or_b32 v17, v139, s54, v17
	v_add_u32_e32 v18, 0xd400, v191
	ds_write2_b32 v18, v16, v17 offset0:68 offset1:198
	v_and_b32_e32 v16, 0xffff, v130
	v_lshrrev_b32_e32 v17, 16, v130
	v_lshl_or_b32 v16, v140, 16, v16
	v_and_or_b32 v17, v140, s54, v17
	v_add_u32_e32 v18, 0xf000, v191
	ds_write2_b32 v18, v16, v17 offset0:96 offset1:226
	v_and_b32_e32 v16, 0xffff, v131
	v_lshrrev_b32_e32 v17, 16, v131
	v_lshl_or_b32 v16, v141, 16, v16
	v_and_or_b32 v17, v141, s54, v17
	v_add_u32_e32 v18, 0xf400, v191
	ds_write2_b32 v18, v16, v17 offset0:100 offset1:230
	s_waitcnt vmcnt(0)
	v_and_b32_e32 v16, 63, v251
	v_lshrrev_b32_e32 v17, 3, v16
	v_mul_u32_u24_e32 v17, 0x90, v17
	v_and_b32_e32 v18, 7, v16
	v_lshl_add_u32 v17, v18, 4, v17
	v_mul_u32_u24_e32 v18, 0x1200, v254
	v_add_u32_e32 v18, 0x12000, v18
	v_add_u32_e32 v17, v17, v18
	v_and_b32_e32 v19, 31, v16
	v_mul_u32_u24_e32 v19, 0x90, v19
	v_lshrrev_b32_e32 v16, 5, v16
	v_lshl_add_u32 v19, v16, 4, v19
	v_add_u32_e32 v19, v19, v18
	ds_write_b128 v17, v[0:3]
	ds_write_b128 v17, v[4:7] offset:1152
	ds_write_b128 v17, v[8:11] offset:2304
	ds_write_b128 v17, v[12:15] offset:3456
	ds_read_b128 v[0:3], v19
	ds_read_b128 v[8:11], v19 offset:32
	ds_read_b128 v[4:7], v19 offset:64
	ds_read_b128 v[12:15], v19 offset:96
	ds_write_b128 v17, v[100:103]
	ds_write_b128 v17, v[104:107] offset:1152
	ds_write_b128 v17, v[108:111] offset:2304
	ds_write_b128 v17, v[112:115] offset:3456
	ds_read_b128 v[100:103], v19
	ds_read_b128 v[108:111], v19 offset:32
	ds_read_b128 v[104:107], v19 offset:64
	ds_read_b128 v[112:115], v19 offset:96
	s_waitcnt lgkmcnt(0)
	s_barrier
	s_cbranch_vccnz .LBB0_354
	s_add_i32 s64, s1, s96
	s_and_b32 s64, s64, 0x780
	s_addk_i32 s64, 0xff80
	v_mov_b32_e32 v96, v97
	v_add_u32_e32 v16, s64, v182
	v_mov_b32_e32 v98, v97
	v_mov_b32_e32 v99, v97
	v_mov_b64_e32 v[80:81], v[96:97]
	v_mov_b64_e32 v[84:85], v[96:97]
	v_mov_b64_e32 v[92:93], v[96:97]
	v_mov_b64_e32 v[88:89], v[96:97]
	s_ashr_i32 s55, s33, 6
	s_and_b32 s69, s33, 3
	v_cmp_lt_i32_e32 vcc, -1, v16
	v_mov_b64_e32 v[82:83], v[98:99]
	v_mov_b64_e32 v[86:87], v[98:99]
	v_mov_b64_e32 v[94:95], v[98:99]
	v_mov_b64_e32 v[90:91], v[98:99]
	s_and_saveexec_b64 s[78:79], vcc
	s_cbranch_execz .LBB0_351
	v_readlane_b32 vcc_lo, v255, 6
	v_readlane_b32 vcc_hi, v255, 7
	v_add_u32_e32 v18, s64, v250
	v_lshl_add_u32 v18, s55, 11, v18
	s_lshl_b32 s94, s69, 7
	v_mov_b64_e32 v[16:17], vcc
	v_mad_i64_i32 v[16:17], vcc, v18, s65, v[16:17]
	v_lshl_add_u64 v[16:17], v[16:17], 0, s[94:95]
	v_mov_b32_e32 v153, v97
	v_lshl_add_u64 v[16:17], v[16:17], 0, v[248:249]
	s_movk_i32 s94, 0x6000
	global_load_dwordx4 v[80:83], v[16:17], off offset:2048
	v_lshl_add_u64 v[16:17], v[16:17], 0, s[94:95]
	global_load_dwordx4 v[84:87], v[16:17], off offset:2048
	v_lshl_add_u64 v[16:17], v[16:17], 0, s[94:95]
	global_load_dwordx4 v[88:91], v[16:17], off offset:2048
	v_lshl_add_u64 v[16:17], v[16:17], 0, s[94:95]
	global_load_dwordx4 v[92:95], v[16:17], off offset:2048

.LBB0_357:
	s_mov_b32 s64, 0xff800000
	v_cndmask_b32_e64 v72, v48, v212, s[2:3]
	v_cndmask_b32_e64 v216, v72, v48, s[4:5]
	v_max3_f32 v48, v158, s64, v157
	v_max3_f32 v48, v48, v156, v155
	v_max3_f32 v48, v48, v154, v119
	v_max3_f32 v48, v48, v118, v99
	v_max3_f32 v48, v48, v71, v70
	v_max3_f32 v48, v48, v69, v68
	v_max3_f32 v48, v48, v67, v66
	v_max3_f32 v48, v48, v65, v64
	v_max3_f32 v48, v48, v32, v33
	v_max3_f32 v48, v48, v34, v35
	v_max3_f32 v48, v48, v36, v37
	v_max3_f32 v48, v48, v38, v39
	v_max3_f32 v48, v48, v40, v41
	v_max3_f32 v48, v48, v42, v43
	v_max3_f32 v48, v48, v44, v45
	v_max3_f32 v48, v48, v46, v47
	v_max3_f32 v48, v48, v16, v17
	v_max3_f32 v48, v48, v18, v19
	v_max3_f32 v48, v48, v20, v21
	v_max3_f32 v48, v48, v22, v23
	v_max3_f32 v48, v48, v24, v25
	v_max3_f32 v48, v48, v26, v27
	v_max3_f32 v48, v48, v28, v29
	v_max3_f32 v48, v48, v30, v31
	v_max3_f32 v48, v48, v0, v1
	v_max3_f32 v48, v48, v2, v3
	v_max3_f32 v48, v48, v4, v5
	v_max3_f32 v48, v48, v6, v7
	v_max3_f32 v48, v48, v8, v9
	v_max3_f32 v48, v48, v10, v11
	v_max3_f32 v48, v48, v12, v13
	v_cndmask_b32_e64 v215, v212, v49, s[4:5]
	v_max3_f32 v48, v48, v14, v15
	v_cndmask_b32_e64 v217, v50, v212, s[6:7]
	v_cndmask_b32_e64 v218, v51, v212, s[8:9]
	v_max3_f32 v48, v48, v216, v215
	v_cndmask_b32_e64 v219, v52, v212, s[10:11]
	v_cndmask_b32_e64 v220, v53, v212, s[12:13]
	v_max3_f32 v48, v48, v217, v218
	v_cndmask_b32_e64 v221, v54, v212, s[14:15]
	v_cndmask_b32_e64 v222, v55, v212, s[16:17]
	v_max3_f32 v48, v48, v219, v220
	v_cndmask_b32_e64 v223, v56, v212, s[18:19]
	v_cndmask_b32_e64 v224, v57, v212, s[20:21]
	v_max3_f32 v48, v48, v221, v222
	v_cndmask_b32_e64 v225, v58, v212, s[22:23]
	v_cndmask_b32_e64 v226, v59, v212, s[24:25]
	v_max3_f32 v48, v48, v223, v224
	v_cndmask_b32_e64 v227, v60, v212, s[26:27]
	v_cndmask_b32_e64 v228, v61, v212, s[28:29]
	v_max3_f32 v48, v48, v225, v226
	v_cndmask_b32_e64 v229, v62, v212, s[30:31]
	v_cndmask_b32_e64 v230, v63, v212, s[34:35]
	v_max3_f32 v48, v48, v227, v228
	v_max3_f32 v48, v48, v229, v230
	ds_bpermute_b32 v49, v188, v48
	v_mul_f32_e32 v96, 0x3fb8aa3b, v214
	v_or_b32_e32 v213, s89, v98
	s_mov_b32 s55, 0x3fb8aa3b
	s_lshl_b32 s94, s69, 1
	s_waitcnt lgkmcnt(0)
	v_max3_f32 v231, v48, v49, v96
	v_sub_f32_e32 v50, v156, v231
	v_exp_f32_e32 v170, v50
	v_sub_f32_e32 v50, v155, v231
	v_exp_f32_e32 v171, v50
	v_sub_f32_e32 v50, v154, v231
	v_exp_f32_e32 v176, v50
	v_sub_f32_e32 v50, v119, v231
	v_exp_f32_e32 v177, v50
	v_sub_f32_e32 v50, v118, v231
	v_sub_f32_e32 v48, v158, v231
	v_exp_f32_e32 v180, v50
	v_sub_f32_e32 v50, v99, v231
	v_exp_f32_e32 v162, v48
	v_sub_f32_e32 v48, v157, v231
	v_exp_f32_e32 v181, v50
	v_sub_f32_e32 v50, v71, v231
	v_exp_f32_e32 v163, v48
	v_exp_f32_e32 v154, v50
	v_sub_f32_e32 v50, v70, v231
	v_exp_f32_e32 v155, v50
	v_sub_f32_e32 v50, v69, v231
	v_sub_f32_e32 v34, v34, v231
	v_exp_f32_e32 v164, v50
	v_sub_f32_e32 v50, v68, v231
	v_exp_f32_e32 v158, v34
	v_sub_f32_e32 v34, v35, v231
	v_exp_f32_e32 v165, v50
	v_sub_f32_e32 v50, v67, v231
	v_exp_f32_e32 v159, v34
	v_sub_f32_e32 v34, v36, v231
	v_pk_add_f32 v[48:49], v[162:163], 0 op_sel_hi:[1,0]
	v_exp_f32_e32 v172, v50
	v_sub_f32_e32 v50, v66, v231
	v_exp_f32_e32 v166, v34
	v_sub_f32_e32 v34, v37, v231
	v_pk_add_f32 v[48:49], v[170:171], v[48:49]
	v_exp_f32_e32 v173, v50
	v_sub_f32_e32 v50, v65, v231
	v_exp_f32_e32 v167, v34
	v_sub_f32_e32 v34, v38, v231
	v_pk_add_f32 v[48:49], v[176:177], v[48:49]
	v_exp_f32_e32 v178, v50
	v_sub_f32_e32 v50, v64, v231
	v_sub_f32_e32 v32, v32, v231
	v_exp_f32_e32 v174, v34
	v_sub_f32_e32 v34, v39, v231
	v_pk_add_f32 v[48:49], v[180:181], v[48:49]
	v_exp_f32_e32 v179, v50
	v_exp_f32_e32 v78, v32
	v_sub_f32_e32 v32, v33, v231
	v_exp_f32_e32 v175, v34
	v_sub_f32_e32 v34, v40, v231
	v_pk_add_f32 v[48:49], v[154:155], v[48:49]
	v_exp_f32_e32 v79, v32
	v_exp_f32_e32 v70, v34
	v_sub_f32_e32 v34, v41, v231
	v_pk_add_f32 v[48:49], v[164:165], v[48:49]
	v_exp_f32_e32 v71, v34
	v_sub_f32_e32 v34, v42, v231
	v_sub_f32_e32 v18, v18, v231
	v_sub_f32_e32 v2, v2, v231
	v_pk_add_f32 v[48:49], v[172:173], v[48:49]
	v_exp_f32_e32 v76, v34
	v_sub_f32_e32 v34, v43, v231
	v_exp_f32_e32 v74, v18
	v_sub_f32_e32 v18, v19, v231
	v_exp_f32_e32 v60, v2
	v_sub_f32_e32 v2, v3, v231
	v_pk_add_f32 v[48:49], v[178:179], v[48:49]
	v_exp_f32_e32 v77, v34
	v_sub_f32_e32 v34, v44, v231
	v_exp_f32_e32 v75, v18
	v_sub_f32_e32 v18, v20, v231
	v_exp_f32_e32 v61, v2
	v_sub_f32_e32 v2, v4, v231
	v_pk_add_f32 v[32:33], v[78:79], v[48:49]
	v_exp_f32_e32 v156, v34
	v_sub_f32_e32 v34, v45, v231
	v_exp_f32_e32 v98, v18
	v_sub_f32_e32 v18, v21, v231
	v_exp_f32_e32 v66, v2
	v_sub_f32_e32 v2, v5, v231
	v_pk_add_f32 v[32:33], v[158:159], v[32:33]
	v_exp_f32_e32 v157, v34
	v_sub_f32_e32 v34, v46, v231
	v_exp_f32_e32 v99, v18
	v_sub_f32_e32 v18, v22, v231
	v_exp_f32_e32 v67, v2
	v_sub_f32_e32 v2, v6, v231
	v_pk_add_f32 v[32:33], v[166:167], v[32:33]
	v_exp_f32_e32 v168, v34
	v_sub_f32_e32 v34, v47, v231
	v_sub_f32_e32 v16, v16, v231
	v_exp_f32_e32 v160, v18
	v_sub_f32_e32 v18, v23, v231
	v_exp_f32_e32 v68, v2
	v_sub_f32_e32 v2, v7, v231
	v_pk_add_f32 v[32:33], v[174:175], v[32:33]
	v_exp_f32_e32 v169, v34
	v_exp_f32_e32 v64, v16
	v_sub_f32_e32 v16, v17, v231
	v_exp_f32_e32 v161, v18
	v_sub_f32_e32 v18, v24, v231
	v_exp_f32_e32 v69, v2
	v_sub_f32_e32 v2, v8, v231
	v_pk_add_f32 v[32:33], v[70:71], v[32:33]
	v_exp_f32_e32 v65, v16
	v_exp_f32_e32 v58, v18
	v_sub_f32_e32 v18, v25, v231
	v_exp_f32_e32 v48, v2
	v_sub_f32_e32 v2, v9, v231
	v_pk_add_f32 v[32:33], v[76:77], v[32:33]
	v_exp_f32_e32 v59, v18
	v_sub_f32_e32 v18, v26, v231
	v_exp_f32_e32 v49, v2
	v_sub_f32_e32 v2, v10, v231
	v_pk_add_f32 v[32:33], v[156:157], v[32:33]
	v_exp_f32_e32 v62, v18
	v_sub_f32_e32 v18, v27, v231
	v_exp_f32_e32 v50, v2
	v_sub_f32_e32 v2, v11, v231
	v_pk_add_f32 v[32:33], v[168:169], v[32:33]
	v_exp_f32_e32 v63, v18
	v_sub_f32_e32 v18, v28, v231
	v_exp_f32_e32 v51, v2
	v_sub_f32_e32 v2, v12, v231
	v_pk_add_f32 v[16:17], v[64:65], v[32:33]
	v_exp_f32_e32 v72, v18
	v_sub_f32_e32 v18, v29, v231
	v_exp_f32_e32 v52, v2
	v_sub_f32_e32 v2, v13, v231
	v_pk_add_f32 v[16:17], v[74:75], v[16:17]
	v_exp_f32_e32 v73, v18
	v_sub_f32_e32 v18, v30, v231
	v_exp_f32_e32 v53, v2
	v_sub_f32_e32 v2, v14, v231
	v_pk_add_f32 v[16:17], v[98:99], v[16:17]
	v_exp_f32_e32 v118, v18
	v_sub_f32_e32 v18, v31, v231
	v_sub_f32_e32 v0, v0, v231
	v_exp_f32_e32 v54, v2
	v_sub_f32_e32 v2, v15, v231
	v_pk_add_f32 v[16:17], v[160:161], v[16:17]
	v_exp_f32_e32 v119, v18
	v_exp_f32_e32 v56, v0
	v_sub_f32_e32 v0, v1, v231
	v_exp_f32_e32 v55, v2
	v_sub_f32_e32 v2, v216, v231
	v_pk_add_f32 v[16:17], v[58:59], v[16:17]
	v_exp_f32_e32 v57, v0
	v_exp_f32_e32 v40, v2
	v_sub_f32_e32 v2, v215, v231
	v_pk_add_f32 v[16:17], v[62:63], v[16:17]
	v_exp_f32_e32 v41, v2
	v_sub_f32_e32 v2, v217, v231
	v_pk_add_f32 v[16:17], v[72:73], v[16:17]
	v_exp_f32_e32 v42, v2
	v_sub_f32_e32 v2, v218, v231
	v_pk_add_f32 v[16:17], v[118:119], v[16:17]
	v_exp_f32_e32 v43, v2
	v_sub_f32_e32 v2, v219, v231
	v_pk_add_f32 v[0:1], v[56:57], v[16:17]
	v_exp_f32_e32 v44, v2
	v_sub_f32_e32 v2, v220, v231
	v_pk_add_f32 v[0:1], v[60:61], v[0:1]
	v_exp_f32_e32 v45, v2
	v_sub_f32_e32 v2, v221, v231
	v_pk_add_f32 v[0:1], v[66:67], v[0:1]
	v_exp_f32_e32 v46, v2
	v_sub_f32_e32 v2, v222, v231
	v_pk_add_f32 v[0:1], v[68:69], v[0:1]
	v_exp_f32_e32 v47, v2
	v_sub_f32_e32 v2, v223, v231
	v_pk_add_f32 v[0:1], v[48:49], v[0:1]
	v_exp_f32_e32 v32, v2
	v_sub_f32_e32 v2, v224, v231
	v_pk_add_f32 v[0:1], v[50:51], v[0:1]
	v_exp_f32_e32 v33, v2
	v_sub_f32_e32 v2, v225, v231
	v_pk_add_f32 v[0:1], v[52:53], v[0:1]
	v_exp_f32_e32 v34, v2
	v_sub_f32_e32 v2, v226, v231
	v_pk_add_f32 v[0:1], v[54:55], v[0:1]
	v_exp_f32_e32 v35, v2
	v_sub_f32_e32 v2, v227, v231
	v_pk_add_f32 v[0:1], v[40:41], v[0:1]
	v_exp_f32_e32 v36, v2
	v_sub_f32_e32 v2, v228, v231
	v_pk_add_f32 v[0:1], v[42:43], v[0:1]
	v_exp_f32_e32 v37, v2
	v_sub_f32_e32 v2, v229, v231
	v_pk_add_f32 v[0:1], v[44:45], v[0:1]
	v_exp_f32_e32 v38, v2
	v_sub_f32_e32 v2, v230, v231
	v_pk_add_f32 v[0:1], v[46:47], v[0:1]
	v_exp_f32_e32 v39, v2
	v_pk_add_f32 v[0:1], v[32:33], v[0:1]
	v_cvt_pk_bf16_f32 v16, v162, v163
	v_cvt_pk_bf16_f32 v17, v170, v171
	v_add_u32_e32 v170, 0x9000, v197
	v_pk_add_f32 v[0:1], v[34:35], v[0:1]
	v_cvt_pk_bf16_f32 v18, v176, v177
	v_cvt_pk_bf16_f32 v19, v180, v181
	v_add_u32_e32 v176, 0xd000, v197
	v_pk_add_f32 v[0:1], v[36:37], v[0:1]
	ds_read2_b64 v[20:23], v176 offset0:32 offset1:34
	v_pk_add_f32 v[0:1], v[38:39], v[0:1]
	v_lshl_add_u64 v[116:117], v[146:147], 0, s[94:95]
	v_add_f32_e32 v0, v0, v1
	ds_bpermute_b32 v1, v188, v0
	s_mov_b32 s97, s0
	v_readlane_b32 s0, v255, 15
	s_waitcnt lgkmcnt(0)
	v_add_f32_e32 v0, v0, v1
	v_fma_f32 v1, v214, s55, -v231
	v_exp_f32_e32 v1, v1
	s_nop 0
	v_add_f32_e32 v214, v1, v0
	ds_read2_b64 v[0:3], v170 offset1:2
	v_cvt_pk_bf16_f32 v162, v154, v155
	v_cvt_pk_bf16_f32 v163, v164, v165
	v_cvt_pk_bf16_f32 v164, v172, v173
	v_cvt_pk_bf16_f32 v165, v178, v179
	ds_read2_b64 v[170:173], v170 offset0:4 offset1:6
	s_waitcnt lgkmcnt(1)
	v_mfma_f32_32x32x16_bf16 v[0:15], v[0:3], v[16:19], 0
	s_waitcnt lgkmcnt(0)
	v_mfma_f32_32x32x16_bf16 v[0:15], v[170:173], v[162:165], v[0:15]
	ds_read2_b64 v[170:173], v176 offset0:36 offset1:38
	v_mfma_f32_32x32x16_bf16 v[16:31], v[20:23], v[16:19], 0
	s_waitcnt lgkmcnt(0)
	v_mfma_f32_32x32x16_bf16 v[16:31], v[170:173], v[162:165], v[16:31]
	v_cvt_pk_bf16_f32 v162, v78, v79
	v_add_u32_e32 v78, 0x9000, v198
	v_cvt_pk_bf16_f32 v163, v158, v159
	v_cvt_pk_bf16_f32 v164, v166, v167
	v_cvt_pk_bf16_f32 v165, v174, v175
	ds_read2_b64 v[170:173], v78 offset1:2
	v_add_u32_e32 v158, 0xd000, v198
	s_waitcnt lgkmcnt(0)
	v_mfma_f32_32x32x16_bf16 v[0:15], v[170:173], v[162:165], v[0:15]
	ds_read2_b64 v[170:173], v158 offset0:32 offset1:34
	v_cvt_pk_bf16_f32 v154, v70, v71
	v_cvt_pk_bf16_f32 v155, v76, v77
	v_cvt_pk_bf16_f32 v156, v156, v157
	v_cvt_pk_bf16_f32 v157, v168, v169
	ds_read2_b64 v[76:79], v78 offset0:4 offset1:6
	s_waitcnt lgkmcnt(0)
	v_mfma_f32_32x32x16_bf16 v[0:15], v[76:79], v[154:157], v[0:15]
	ds_read2_b64 v[76:79], v158 offset0:36 offset1:38
	v_mfma_f32_32x32x16_bf16 v[16:31], v[170:173], v[162:165], v[16:31]
	s_waitcnt lgkmcnt(0)
	v_mfma_f32_32x32x16_bf16 v[16:31], v[76:79], v[154:157], v[16:31]
	v_cvt_pk_bf16_f32 v76, v64, v65
	v_add_u32_e32 v64, 0x9000, v199
	v_cvt_pk_bf16_f32 v77, v74, v75
	v_cvt_pk_bf16_f32 v78, v98, v99
	v_cvt_pk_bf16_f32 v79, v160, v161
	ds_read2_b64 v[154:157], v64 offset1:2
	v_add_u32_e32 v74, 0xd000, v199
	s_waitcnt lgkmcnt(0)
	v_mfma_f32_32x32x16_bf16 v[0:15], v[154:157], v[76:79], v[0:15]
	ds_read2_b64 v[154:157], v74 offset0:32 offset1:34
	v_cvt_pk_bf16_f32 v70, v58, v59
	v_cvt_pk_bf16_f32 v71, v62, v63
	v_cvt_pk_bf16_f32 v72, v72, v73
	v_cvt_pk_bf16_f32 v73, v118, v119
	ds_read2_b64 v[62:65], v64 offset0:4 offset1:6
	v_or_b32_e32 v118, s0, v153
	s_waitcnt lgkmcnt(0)
	v_mfma_f32_32x32x16_bf16 v[0:15], v[62:65], v[70:73], v[0:15]
	ds_read2_b64 v[62:65], v74 offset0:36 offset1:38
	v_cvt_pk_bf16_f32 v56, v56, v57
	v_cvt_pk_bf16_f32 v57, v60, v61
	v_cvt_pk_bf16_f32 v58, v66, v67
	v_cvt_pk_bf16_f32 v59, v68, v69
	v_and_b32_e32 v67, 0xffff0000, v103
	v_and_b32_e32 v66, 0xffff0000, v107
	v_mfma_f32_32x32x16_bf16 v[16:31], v[154:157], v[76:79], v[16:31]
	v_lshlrev_b32_e32 v155, 16, v100
	v_lshlrev_b32_e32 v154, 16, v104
	v_and_b32_e32 v79, 0xffff0000, v102
	v_mul_f32_e64 v156, v154, v154
	v_mul_f32_e64 v157, v155, v155
	v_and_b32_e32 v78, 0xffff0000, v106
	v_pk_mul_f32 v[98:99], v[78:79], v[78:79]
	v_pk_mul_f32 v[68:69], v[66:67], v[66:67]
	s_waitcnt lgkmcnt(0)
	v_mfma_f32_32x32x16_bf16 v[16:31], v[62:65], v[70:73], v[16:31]
	v_add_u32_e32 v64, 0x9000, v200
	ds_read2_b64 v[60:63], v64 offset1:2
	v_add_u32_e32 v65, 0xd000, v200
	v_lshlrev_b32_e32 v71, 16, v102
	v_lshlrev_b32_e32 v102, 16, v105
	v_lshlrev_b32_e32 v70, 16, v106
	v_pk_mul_f32 v[72:73], v[70:71], v[70:71]
	s_waitcnt lgkmcnt(0)
	v_mfma_f32_32x32x16_bf16 v[0:15], v[60:63], v[56:59], v[0:15]
	ds_read2_b64 v[60:63], v65 offset0:32 offset1:34
	v_cvt_pk_bf16_f32 v48, v48, v49
	v_cvt_pk_bf16_f32 v49, v50, v51
	v_cvt_pk_bf16_f32 v50, v52, v53
	v_cvt_pk_bf16_f32 v51, v54, v55
	ds_read2_b64 v[52:55], v64 offset0:4 offset1:6
	s_waitcnt lgkmcnt(0)
	v_mfma_f32_32x32x16_bf16 v[0:15], v[52:55], v[48:51], v[0:15]
	ds_read2_b64 v[52:55], v65 offset0:36 offset1:38
	v_cvt_pk_bf16_f32 v40, v40, v41
	v_cvt_pk_bf16_f32 v41, v42, v43
	v_cvt_pk_bf16_f32 v42, v44, v45
	v_cvt_pk_bf16_f32 v43, v46, v47
	v_mfma_f32_32x32x16_bf16 v[16:31], v[60:63], v[56:59], v[16:31]
	v_lshlrev_b32_e32 v59, 16, v103
	v_lshlrev_b32_e32 v103, 16, v101
	v_lshlrev_b32_e32 v58, 16, v107
	v_mul_f32_e64 v106, v102, v102
	v_mul_f32_e64 v107, v103, v103
	v_pk_mul_f32 v[60:61], v[58:59], v[58:59]
	s_waitcnt lgkmcnt(0)
	v_mfma_f32_32x32x16_bf16 v[16:31], v[52:55], v[48:51], v[16:31]
	v_add_u32_e32 v48, 0x9000, v201
	ds_read2_b64 v[44:47], v48 offset1:2
	v_add_u32_e32 v49, 0xd000, v201
	s_waitcnt lgkmcnt(0)
	v_mfma_f32_32x32x16_bf16 v[0:15], v[44:47], v[40:43], v[0:15]
	ds_read2_b64 v[44:47], v49 offset0:32 offset1:34
	v_cvt_pk_bf16_f32 v32, v32, v33
	v_cvt_pk_bf16_f32 v33, v34, v35
	v_cvt_pk_bf16_f32 v34, v36, v37
	v_cvt_pk_bf16_f32 v35, v38, v39
	ds_read2_b64 v[36:39], v48 offset0:4 offset1:6
	s_waitcnt lgkmcnt(0)
	v_mfma_f32_32x32x16_bf16 v[0:15], v[36:39], v[32:35], v[0:15]
	ds_read2_b64 v[36:39], v49 offset0:36 offset1:38
	v_mfma_f32_32x32x16_bf16 v[16:31], v[44:47], v[40:43], v[16:31]
	v_lshlrev_b32_e32 v42, 16, v112
	v_lshlrev_b32_e32 v43, 16, v108
	v_mul_f32_e64 v54, v42, v42
	v_mul_f32_e64 v55, v43, v43
	s_waitcnt lgkmcnt(0)
	v_mfma_f32_32x32x16_bf16 v[16:31], v[36:39], v[32:35], v[16:31]
	v_div_scale_f32 v32, s[68:69], v214, v214, 1.0
	v_rcp_f32_e32 v33, v32
	v_lshlrev_b32_e32 v38, 16, v113
	v_mov_b32_e32 v41, v38
	v_lshlrev_b32_e32 v39, 16, v109
	v_fma_f32 v34, -v32, v33, 1.0
	v_fmac_f32_e32 v33, v34, v33
	v_div_scale_f32 v34, vcc, 1.0, v214, 1.0
	v_mul_f32_e32 v35, v34, v33
	v_fma_f32 v36, -v32, v35, v34
	v_fmac_f32_e32 v35, v36, v33
	v_fma_f32 v32, -v32, v35, v34
	v_div_fmas_f32 v32, v32, v33, v35
	v_div_fixup_f32 v34, v32, v214, 1.0
	v_mul_f32_e32 v0, v0, v34
	v_mul_f32_e32 v1, v1, v34
	v_cvt_pk_bf16_f32 v0, v0, v1
	v_mul_f32_e32 v1, v2, v34
	v_mad_i64_i32 v[32:33], s[68:69], v213, s65, v[116:117]
	v_and_b32_e32 v36, 63, v251
	v_and_b32_e32 v35, 31, v251
	v_lshrrev_b32_e32 v37, 5, v36
	v_lshlrev_b32_e32 v37, 3, v37
	s_movk_i32 s58, 0x90
	v_mad_u32_u24 v35, v35, s58, v37
	s_movk_i32 s59, 0x1200
	v_mad_u32_u24 v35, v254, s59, v35
	v_add_u32_e32 v35, 0x12000, v35
	v_lshrrev_b32_e32 v37, 3, v36
	v_and_b32_e32 v40, 7, v36
	v_lshlrev_b32_e32 v40, 4, v40
	v_mad_u32_u24 v36, v37, s58, v40
	v_mad_u32_u24 v36, v254, s59, v36
	v_add_u32_e32 v36, 0x12000, v36
	s_movk_i32 s58, 0xc00
	v_mad_u32_u24 v37, v37, s58, v40
	v_readfirstlane_b32 s56, v32
	v_readfirstlane_b32 s57, v33
	v_mul_f32_e32 v2, v3, v34
	v_cvt_pk_bf16_f32 v1, v1, v2
	ds_write_b64 v35, v[0:1]
	v_mul_f32_e32 v0, v4, v34
	v_mul_f32_e32 v1, v5, v34
	v_cvt_pk_bf16_f32 v0, v0, v1
	v_mul_f32_e32 v1, v6, v34
	v_mul_f32_e32 v2, v7, v34
	v_cvt_pk_bf16_f32 v1, v1, v2
	ds_write_b64 v35, v[0:1] offset:16
	v_mul_f32_e32 v0, v8, v34
	v_mul_f32_e32 v1, v9, v34
	v_cvt_pk_bf16_f32 v0, v0, v1
	v_mul_f32_e32 v1, v10, v34
	v_mul_f32_e32 v2, v11, v34
	v_cvt_pk_bf16_f32 v1, v1, v2
	ds_write_b64 v35, v[0:1] offset:32
	v_mul_f32_e32 v0, v12, v34
	v_mul_f32_e32 v1, v13, v34
	v_cvt_pk_bf16_f32 v0, v0, v1
	v_mul_f32_e32 v1, v14, v34
	v_mul_f32_e32 v2, v15, v34
	v_cvt_pk_bf16_f32 v1, v1, v2
	ds_write_b64 v35, v[0:1] offset:48
	v_mul_f32_e32 v0, v16, v34
	v_mul_f32_e32 v1, v17, v34
	v_cvt_pk_bf16_f32 v0, v0, v1
	v_mul_f32_e32 v1, v18, v34
	v_mul_f32_e32 v2, v19, v34
	v_cvt_pk_bf16_f32 v1, v1, v2
	ds_write_b64 v35, v[0:1] offset:64
	v_mul_f32_e32 v0, v20, v34
	v_mul_f32_e32 v1, v21, v34
	v_cvt_pk_bf16_f32 v0, v0, v1
	v_mul_f32_e32 v1, v22, v34
	v_mul_f32_e32 v2, v23, v34
	v_cvt_pk_bf16_f32 v1, v1, v2
	ds_write_b64 v35, v[0:1] offset:80
	v_mul_f32_e32 v0, v24, v34
	v_mul_f32_e32 v1, v25, v34
	v_cvt_pk_bf16_f32 v0, v0, v1
	v_mul_f32_e32 v1, v26, v34
	v_mul_f32_e32 v2, v27, v34
	v_cvt_pk_bf16_f32 v1, v1, v2
	ds_write_b64 v35, v[0:1] offset:96
	v_mul_f32_e32 v0, v28, v34
	v_mul_f32_e32 v1, v29, v34
	v_cvt_pk_bf16_f32 v0, v0, v1
	v_mul_f32_e32 v1, v30, v34
	v_mul_f32_e32 v2, v31, v34
	v_cvt_pk_bf16_f32 v1, v1, v2
	ds_write_b64 v35, v[0:1] offset:112
	s_waitcnt lgkmcnt(0)
	ds_read_b128 v[0:3], v36
	ds_read_b128 v[4:7], v36 offset:1152
	ds_read_b128 v[8:11], v36 offset:2304
	ds_read_b128 v[12:15], v36 offset:3456
	s_waitcnt lgkmcnt(3)
	global_store_dwordx4 v37, v[0:3], s[56:57]
	s_add_u32 s56, s56, 0x6000
	s_addc_u32 s57, s57, 0
	s_waitcnt lgkmcnt(2)
	global_store_dwordx4 v37, v[4:7], s[56:57]
	s_add_u32 s56, s56, 0x6000
	s_addc_u32 s57, s57, 0
	s_waitcnt lgkmcnt(1)
	global_store_dwordx4 v37, v[8:11], s[56:57]
	s_add_u32 s56, s56, 0x6000
	s_addc_u32 s57, s57, 0
	s_waitcnt lgkmcnt(0)
	global_store_dwordx4 v37, v[12:15], s[56:57]
	s_nop 1
	s_and_b64 vcc, exec, s[76:77]
	s_cbranch_vccnz .Lvpf_skip
	s_lshl_b32 s58, s33, 5
	s_and_b32 s58, s58, 0x780
	s_addk_i32 s58, 0xff80
	v_add_u32_e32 v16, s58, v183
	v_cmp_lt_i32_e32 vcc, -1, v16
	v_mov_b32_e32 v122, 0
	v_mov_b32_e32 v123, 0
	v_mov_b32_e32 v124, 0
	v_mov_b32_e32 v125, 0
	v_mov_b32_e32 v128, 0
	v_mov_b32_e32 v129, 0
	v_mov_b32_e32 v130, 0
	v_mov_b32_e32 v131, 0
	v_mov_b32_e32 v132, 0
	v_mov_b32_e32 v133, 0
	v_mov_b32_e32 v134, 0
	v_mov_b32_e32 v135, 0
	v_mov_b32_e32 v136, 0
	v_mov_b32_e32 v137, 0
	v_mov_b32_e32 v138, 0
	v_mov_b32_e32 v139, 0
	s_and_saveexec_b64 s[80:81], vcc
	s_cbranch_execz .Lvpf_join
	v_readlane_b32 vcc_lo, v255, 6
	v_readlane_b32 vcc_hi, v255, 7
	s_ashr_i32 s59, s33, 6
	v_add_u32_e32 v18, s58, v250
	v_lshl_add_u32 v18, s59, 11, v18
	s_and_b32 s58, s33, 3
	s_lshl_b32 s58, s58, 7
	s_mov_b32 s59, 0
	v_mov_b64_e32 v[16:17], vcc
	v_mad_i64_i32 v[16:17], vcc, v18, s65, v[16:17]
	v_lshl_add_u64 v[16:17], v[16:17], 0, s[58:59]
	v_lshl_add_u64 v[16:17], v[16:17], 0, v[248:249]
	s_movk_i32 s58, 0x6000
	global_load_dwordx4 v[122:125], v[16:17], off offset:2560
	v_lshl_add_u64 v[16:17], v[16:17], 0, s[58:59]
	global_load_dwordx4 v[128:131], v[16:17], off offset:2560
	v_lshl_add_u64 v[16:17], v[16:17], 0, s[58:59]
	global_load_dwordx4 v[132:135], v[16:17], off offset:2560
	v_lshl_add_u64 v[16:17], v[16:17], 0, s[58:59]
	global_load_dwordx4 v[136:139], v[16:17], off offset:2560
.Lvpf_join:
	s_or_b64 exec, exec, s[80:81]
.Lvpf_skip:
	ds_read_b128 v[0:3], v243 offset:16
	s_nop 0
	ds_read_b128 v[16:19], v243
	ds_read_b128 v[4:7], v243 offset:144
	ds_read_b128 v[20:23], v243 offset:128
	v_lshlrev_b32_e32 v28, 5, v118
	v_or_b32_e32 v8, v28, v126
	v_lshlrev_b32_e32 v29, 2, v8
	ds_read_b128 v[8:11], v252 offset:6144
	ds_read_b128 v[24:27], v252 offset:2048
	ds_read_b128 v[12:15], v252 offset:24192
	ds_read_b128 v[44:47], v252 offset:20096
	v_or_b32_e32 v28, v28, v127
	v_lshlrev_b32_e32 v119, 2, v28
	v_lshlrev_b32_e32 v30, 16, v115
	v_and_b32_e32 v28, 0xffff0000, v115
	v_mov_b32_e32 v32, v28
	v_mov_b32_e32 v33, v30
	v_pk_mul_f32 v[48:49], v[32:33], v[32:33]
	v_lshlrev_b32_e32 v34, 16, v114
	v_and_b32_e32 v32, 0xffff0000, v114
	v_mov_b32_e32 v36, v32
	v_mov_b32_e32 v37, v34
	v_pk_mul_f32 v[50:51], v[36:37], v[36:37]
	v_and_b32_e32 v36, 0xffff0000, v113
	v_mov_b32_e32 v40, v36
	v_and_b32_e32 v113, 0xffff0000, v101
	v_and_b32_e32 v101, 0xffff0000, v100
	v_and_b32_e32 v100, 0xffff0000, v104
	v_pk_mul_f32 v[52:53], v[40:41], v[40:41]
	v_and_b32_e32 v40, 0xffff0000, v112
	v_and_b32_e32 v112, 0xffff0000, v105
	v_pk_mul_f32 v[104:105], v[100:101], v[100:101]
	v_pk_mul_f32 v[114:115], v[112:113], v[112:113]
	v_and_b32_e32 v41, 0xffff0000, v108
	v_pk_mul_f32 v[56:57], v[40:41], v[40:41]
	v_and_b32_e32 v37, 0xffff0000, v109
	v_lshlrev_b32_e32 v35, 16, v110
	v_and_b32_e32 v33, 0xffff0000, v110
	v_lshlrev_b32_e32 v31, 16, v111
	v_and_b32_e32 v29, 0xffff0000, v111
	s_andn2_b64 vcc, exec, s[78:79]
	s_waitcnt lgkmcnt(0)
	v_mov_b32_e32 v75, v0
	v_add_f32_e32 v0, v157, v105
	v_add_f32_e32 v0, v107, v0
	v_add_f32_e32 v0, v115, v0
	v_add_f32_e32 v0, v73, v0
	v_add_f32_e32 v0, v99, v0
	v_add_f32_e32 v0, v61, v0
	v_add_f32_e32 v0, v69, v0
	v_add_f32_e32 v0, v55, v0
	v_add_f32_e32 v0, v57, v0
	v_fmac_f32_e32 v0, v39, v39
	v_fmac_f32_e32 v0, v37, v37
	v_fmac_f32_e32 v0, v35, v35
	v_fmac_f32_e32 v0, v33, v33
	v_fmac_f32_e32 v0, v31, v31
	v_fmac_f32_e32 v0, v29, v29
	v_add_f32_e32 v0, v156, v0
	v_add_f32_e32 v0, v104, v0
	v_add_f32_e32 v0, v106, v0
	v_add_f32_e32 v0, v114, v0
	v_add_f32_e32 v0, v72, v0
	v_add_f32_e32 v0, v98, v0
	v_add_f32_e32 v0, v60, v0
	v_add_f32_e32 v0, v68, v0
	v_add_f32_e32 v0, v54, v0
	v_add_f32_e32 v0, v56, v0
	v_add_f32_e32 v0, v53, v0
	v_add_f32_e32 v0, v52, v0
	v_add_f32_e32 v0, v51, v0
	v_add_f32_e32 v0, v50, v0
	v_add_f32_e32 v0, v49, v0
	v_add_f32_e32 v0, v48, v0
	v_mov_b32_e32 v63, v2
	ds_bpermute_b32 v2, v188, v0
	s_waitcnt lgkmcnt(0)
	v_mov_b32_e32 v74, v4
	s_waitcnt lgkmcnt(0)
	v_mov_b32_e32 v158, v20
	s_waitcnt lgkmcnt(0)
	v_mov_b32_e32 v159, v16
	v_mov_b32_e32 v160, v24
	s_waitcnt lgkmcnt(0)
	v_add_f32_e32 v0, v0, v2
	v_fmamk_f32 v0, v0, 0x3c800000, v189
	v_rsq_f32_e32 v0, v0
	v_mov_b32_e32 v161, v44
	v_mov_b32_e32 v50, v44
	v_mov_b32_e32 v51, v24
	v_mul_f32_e32 v4, 0x3e38aa3b, v0
	v_pk_mul_f32 v[48:49], v[4:5], v[154:155] op_sel_hi:[0,1]
	v_pk_mul_f32 v[48:49], v[158:159], v[48:49]
	v_mov_b32_e32 v108, v22
	v_pk_mul_f32 v[50:51], v[50:51], v[48:49]
	v_pk_mul_f32 v[48:49], v[160:161], v[48:49]
	v_mov_b32_e32 v16, v21
	v_add_f32_e32 v22, v48, v49
	v_pk_mul_f32 v[48:49], v[4:5], v[100:101] op_sel_hi:[0,1]
	v_pk_mul_f32 v[16:17], v[16:17], v[48:49]
	v_mov_b32_e32 v24, v45
	v_mov_b32_e32 v44, v25
	v_pk_mul_f32 v[20:21], v[24:25], v[16:17]
	v_pk_mul_f32 v[16:17], v[44:45], v[16:17]
	v_mov_b32_e32 v109, v18
	v_add_f32_e32 v25, v16, v17
	v_pk_mul_f32 v[16:17], v[4:5], v[102:103] op_sel_hi:[0,1]
	v_mov_b32_e32 v110, v26
	v_mov_b32_e32 v111, v46
	v_sub_f32_e32 v24, v21, v20
	v_pk_mul_f32 v[16:17], v[16:17], v[108:109]
	v_mov_b32_e32 v20, v46
	v_mov_b32_e32 v21, v26
	v_pk_mul_f32 v[20:21], v[16:17], v[20:21]
	v_pk_mul_f32 v[16:17], v[16:17], v[110:111]
	v_sub_f32_e32 v20, v21, v20
	v_add_f32_e32 v21, v16, v17
	v_pk_mul_f32 v[16:17], v[4:5], v[112:113] op_sel_hi:[0,1]
	v_mov_b32_e32 v18, v23
	v_pk_mul_f32 v[16:17], v[16:17], v[18:19]
	v_mov_b32_e32 v26, v47
	v_mov_b32_e32 v46, v27
	v_pk_mul_f32 v[18:19], v[16:17], v[26:27]
	v_pk_mul_f32 v[16:17], v[16:17], v[46:47]
	v_mov_b32_e32 v76, v8
	v_add_f32_e32 v26, v16, v17
	v_pk_mul_f32 v[16:17], v[4:5], v[70:71] op_sel_hi:[0,1]
	v_mov_b32_e32 v77, v12
	v_sub_f32_e32 v23, v19, v18
	v_pk_mul_f32 v[16:17], v[16:17], v[74:75]
	v_mov_b32_e32 v18, v12
	v_mov_b32_e32 v19, v8
	v_pk_mul_f32 v[18:19], v[16:17], v[18:19]
	v_pk_mul_f32 v[16:17], v[16:17], v[76:77]
	v_sub_f32_e32 v18, v19, v18
	v_add_f32_e32 v19, v16, v17
	v_pk_mul_f32 v[16:17], v[4:5], v[78:79] op_sel_hi:[0,1]
	v_mov_b32_e32 v0, v5
	v_pk_mul_f32 v[0:1], v[16:17], v[0:1]
	v_mov_b32_e32 v8, v13
	v_pk_mul_f32 v[16:17], v[0:1], v[8:9]
	v_mov_b32_e32 v12, v9
	v_sub_f32_e32 v5, v17, v16
	v_pk_mul_f32 v[0:1], v[0:1], v[12:13]
	v_mov_b32_e32 v62, v6
	v_add_f32_e32 v12, v0, v1
	v_pk_mul_f32 v[0:1], v[4:5], v[58:59] op_sel_hi:[0,1]
	v_mov_b32_e32 v64, v10
	v_mov_b32_e32 v65, v14
	v_pk_mul_f32 v[0:1], v[0:1], v[62:63]
	v_mov_b32_e32 v8, v14
	v_mov_b32_e32 v9, v10
	v_pk_mul_f32 v[8:9], v[0:1], v[8:9]
	v_pk_mul_f32 v[0:1], v[0:1], v[64:65]
	v_sub_f32_e32 v8, v9, v8
	v_add_f32_e32 v9, v0, v1
	v_pk_mul_f32 v[0:1], v[4:5], v[66:67] op_sel_hi:[0,1]
	v_mov_b32_e32 v2, v7
	v_pk_mul_f32 v[0:1], v[0:1], v[2:3]
	v_mov_b32_e32 v10, v15
	v_mov_b32_e32 v14, v11
	v_pk_mul_f32 v[2:3], v[0:1], v[10:11]
	v_pk_mul_f32 v[0:1], v[0:1], v[14:15]
	v_sub_f32_e32 v6, v51, v50
	v_sub_f32_e32 v2, v3, v2
	v_add_f32_e32 v0, v0, v1
	v_cvt_pk_bf16_f32 v48, v6, v24
	v_cvt_pk_bf16_f32 v49, v20, v23
	v_cvt_pk_bf16_f32 v50, v18, v5
	v_cvt_pk_bf16_f32 v51, v8, v2
	v_cvt_pk_bf16_f32 v98, v22, v25
	v_cvt_pk_bf16_f32 v99, v21, v26
	v_cvt_pk_bf16_f32 v100, v19, v12
	v_cvt_pk_bf16_f32 v101, v9, v0
	ds_read_b128 v[0:3], v243 offset:80
	ds_read_b128 v[6:9], v243 offset:64
	ds_read_b128 v[10:13], v243 offset:208
	ds_read_b128 v[14:17], v243 offset:192
	v_pk_mul_f32 v[18:19], v[4:5], v[42:43] op_sel_hi:[0,1]
	s_waitcnt lgkmcnt(0)
	v_mov_b32_e32 v21, v6
	s_waitcnt lgkmcnt(0)
	v_mov_b32_e32 v20, v14
	v_pk_mul_f32 v[26:27], v[18:19], v[20:21]
	ds_read_b128 v[18:21], v252 offset:14336
	ds_read_b128 v[22:25], v252 offset:10240
	ds_read_b128 v[42:45], v252 offset:32384
	ds_read_b128 v[52:55], v252 offset:28288
	v_mov_b32_e32 v6, v15
	s_waitcnt lgkmcnt(0)
	v_mov_b32_e32 v47, v22
	s_waitcnt lgkmcnt(0)
	v_mov_b32_e32 v46, v52
	v_pk_mul_f32 v[46:47], v[26:27], v[46:47]
	s_nop 0
	v_sub_f32_e32 v5, v47, v46
	v_mov_b32_e32 v46, v22
	v_mov_b32_e32 v47, v52
	v_pk_mul_f32 v[26:27], v[26:27], v[46:47]
	v_mov_b32_e32 v22, v53
	v_add_f32_e32 v46, v26, v27
	v_pk_mul_f32 v[26:27], v[4:5], v[40:41] op_sel_hi:[0,1]
	v_pk_mul_f32 v[6:7], v[26:27], v[6:7]
	v_mov_b32_e32 v52, v23
	v_pk_mul_f32 v[14:15], v[6:7], v[22:23]
	v_pk_mul_f32 v[6:7], v[6:7], v[52:53]
	v_sub_f32_e32 v22, v15, v14
	v_add_f32_e32 v23, v6, v7
	v_pk_mul_f32 v[6:7], v[4:5], v[38:39] op_sel_hi:[0,1]
	v_mov_b32_e32 v14, v16
	v_mov_b32_e32 v15, v8
	v_pk_mul_f32 v[6:7], v[6:7], v[14:15]
	v_mov_b32_e32 v14, v54
	v_mov_b32_e32 v15, v24
	v_pk_mul_f32 v[14:15], v[6:7], v[14:15]
	v_mov_b32_e32 v8, v17
	v_sub_f32_e32 v16, v15, v14
	v_mov_b32_e32 v14, v24
	v_mov_b32_e32 v15, v54
	v_pk_mul_f32 v[6:7], v[6:7], v[14:15]
	v_mov_b32_e32 v24, v55
	v_add_f32_e32 v14, v6, v7
	v_pk_mul_f32 v[6:7], v[4:5], v[36:37] op_sel_hi:[0,1]
	v_pk_mul_f32 v[6:7], v[6:7], v[8:9]
	v_mov_b32_e32 v54, v25
	v_pk_mul_f32 v[8:9], v[6:7], v[24:25]
	v_pk_mul_f32 v[6:7], v[6:7], v[54:55]
	v_sub_f32_e32 v15, v9, v8
	v_add_f32_e32 v17, v6, v7
	v_pk_mul_f32 v[6:7], v[4:5], v[34:35] op_sel_hi:[0,1]
	s_waitcnt lgkmcnt(0)
	v_mov_b32_e32 v8, v10
	s_waitcnt lgkmcnt(0)
	v_mov_b32_e32 v9, v0
	v_pk_mul_f32 v[6:7], v[6:7], v[8:9]
	v_mov_b32_e32 v8, v42
	v_mov_b32_e32 v9, v18
	v_pk_mul_f32 v[8:9], v[6:7], v[8:9]
	v_mov_b32_e32 v0, v11
	v_sub_f32_e32 v10, v9, v8
	v_mov_b32_e32 v8, v18
	v_mov_b32_e32 v9, v42
	v_pk_mul_f32 v[6:7], v[6:7], v[8:9]
	v_mov_b32_e32 v18, v43
	v_add_f32_e32 v8, v6, v7
	v_pk_mul_f32 v[6:7], v[4:5], v[32:33] op_sel_hi:[0,1]
	v_pk_mul_f32 v[0:1], v[6:7], v[0:1]
	v_mov_b32_e32 v42, v19
	v_pk_mul_f32 v[6:7], v[0:1], v[18:19]
	v_pk_mul_f32 v[0:1], v[0:1], v[42:43]
	v_sub_f32_e32 v9, v7, v6
	v_add_f32_e32 v11, v0, v1
	v_pk_mul_f32 v[0:1], v[4:5], v[30:31] op_sel_hi:[0,1]
	v_mov_b32_e32 v6, v12
	v_mov_b32_e32 v7, v2
	v_pk_mul_f32 v[0:1], v[0:1], v[6:7]
	v_mov_b32_e32 v6, v44
	v_mov_b32_e32 v7, v20
	v_pk_mul_f32 v[6:7], v[0:1], v[6:7]
	v_mov_b32_e32 v2, v13
	v_sub_f32_e32 v12, v7, v6
	v_mov_b32_e32 v6, v20
	v_mov_b32_e32 v7, v44
	v_pk_mul_f32 v[0:1], v[0:1], v[6:7]
	v_mov_b32_e32 v20, v45
	v_add_f32_e32 v6, v0, v1
	v_pk_mul_f32 v[0:1], v[4:5], v[28:29] op_sel_hi:[0,1]
	v_pk_mul_f32 v[0:1], v[0:1], v[2:3]
	v_mov_b32_e32 v44, v21
	v_pk_mul_f32 v[2:3], v[0:1], v[20:21]
	v_pk_mul_f32 v[0:1], v[0:1], v[44:45]
	v_sub_f32_e32 v2, v3, v2
	v_add_f32_e32 v0, v0, v1
	v_cvt_pk_bf16_f32 v102, v5, v22
	v_cvt_pk_bf16_f32 v103, v16, v15
	v_cvt_pk_bf16_f32 v104, v10, v9
	v_cvt_pk_bf16_f32 v105, v12, v2
	v_cvt_pk_bf16_f32 v106, v46, v23
	v_cvt_pk_bf16_f32 v107, v14, v17
	v_cvt_pk_bf16_f32 v108, v8, v11
	v_cvt_pk_bf16_f32 v109, v6, v0
	ds_read_b128 v[0:3], v202
	ds_read_b128 v[4:7], v202 offset:32
	s_waitcnt lgkmcnt(1)
	v_mfma_f32_32x32x16_bf16 v[64:79], v[0:3], v[48:51], 0
	ds_read_b128 v[0:3], v202 offset:64
	s_waitcnt lgkmcnt(1)
	v_mfma_f32_32x32x16_bf16 v[64:79], v[4:7], v[102:105], v[64:79]
	s_waitcnt lgkmcnt(0)
	v_mfma_f32_32x32x16_bf16 v[64:79], v[0:3], v[98:101], v[64:79]
	ds_read_b128 v[0:3], v202 offset:96
	s_waitcnt lgkmcnt(0)
	v_mfma_f32_32x32x16_bf16 v[64:79], v[0:3], v[106:109], v[64:79]
	ds_read_b128 v[0:3], v203
	ds_read_b128 v[4:7], v203 offset:32
	s_waitcnt lgkmcnt(1)
	v_mfma_f32_32x32x16_bf16 v[32:47], v[0:3], v[48:51], 0
	ds_read_b128 v[0:3], v203 offset:64
	s_waitcnt lgkmcnt(1)
	v_mfma_f32_32x32x16_bf16 v[32:47], v[4:7], v[102:105], v[32:47]
	s_waitcnt lgkmcnt(0)
	v_mfma_f32_32x32x16_bf16 v[32:47], v[0:3], v[98:101], v[32:47]
	ds_read_b128 v[0:3], v203 offset:96
	s_waitcnt lgkmcnt(0)
	v_mfma_f32_32x32x16_bf16 v[32:47], v[0:3], v[106:109], v[32:47]
	ds_read_b128 v[0:3], v204
	ds_read_b128 v[4:7], v204 offset:32
	s_waitcnt lgkmcnt(1)
	v_mfma_f32_32x32x16_bf16 v[16:31], v[0:3], v[48:51], 0
	ds_read_b128 v[0:3], v204 offset:64
	s_waitcnt lgkmcnt(1)
	v_mfma_f32_32x32x16_bf16 v[16:31], v[4:7], v[102:105], v[16:31]
	s_waitcnt lgkmcnt(0)
	v_mfma_f32_32x32x16_bf16 v[16:31], v[0:3], v[98:101], v[16:31]
	ds_read_b128 v[0:3], v204 offset:96
	s_waitcnt lgkmcnt(0)
	v_mfma_f32_32x32x16_bf16 v[16:31], v[0:3], v[106:109], v[16:31]
	ds_read_b128 v[0:3], v205
	ds_read_b128 v[52:55], v205 offset:32
	s_waitcnt lgkmcnt(1)
	v_mfma_f32_32x32x16_bf16 v[0:15], v[0:3], v[48:51], 0
	s_waitcnt lgkmcnt(0)
	v_mfma_f32_32x32x16_bf16 v[0:15], v[52:55], v[102:105], v[0:15]
	ds_read_b128 v[52:55], v205 offset:64
	s_waitcnt lgkmcnt(0)
	v_mfma_f32_32x32x16_bf16 v[0:15], v[52:55], v[98:101], v[0:15]
	ds_read_b128 v[52:55], v205 offset:96
	s_waitcnt lgkmcnt(0)
	v_mfma_f32_32x32x16_bf16 v[0:15], v[52:55], v[106:109], v[0:15]
	ds_read_b128 v[52:55], v206
	ds_read_b128 v[110:113], v206 offset:32
	s_waitcnt lgkmcnt(1)
	v_mfma_f32_32x32x16_bf16 v[48:63], v[52:55], v[48:51], 0
	s_waitcnt lgkmcnt(0)
	v_mfma_f32_32x32x16_bf16 v[48:63], v[110:113], v[102:105], v[48:63]
	ds_read_b128 v[102:105], v206 offset:64
	s_waitcnt lgkmcnt(0)
	v_mfma_f32_32x32x16_bf16 v[48:63], v[102:105], v[98:101], v[48:63]
	ds_read_b128 v[98:101], v206 offset:96
	s_waitcnt lgkmcnt(0)
	v_mfma_f32_32x32x16_bf16 v[48:63], v[98:101], v[106:109], v[48:63]
	s_cbranch_vccz .LBB0_346
	v_cndmask_b32_e64 v98, v212, v64, s[2:3]
	v_cndmask_b32_e64 v105, v65, v212, s[4:5]
	v_cndmask_b32_e64 v104, v212, v66, s[6:7]
	v_cndmask_b32_e64 v103, v212, v67, s[8:9]
	v_cndmask_b32_e64 v102, v212, v68, s[10:11]
	v_cndmask_b32_e64 v101, v212, v69, s[12:13]
	v_cndmask_b32_e64 v100, v212, v70, s[14:15]
	v_cndmask_b32_e64 v99, v212, v71, s[16:17]
	v_cndmask_b32_e64 v71, v212, v72, s[18:19]
	v_cndmask_b32_e64 v70, v212, v73, s[20:21]
	v_cndmask_b32_e64 v69, v212, v74, s[22:23]
	v_cndmask_b32_e64 v68, v212, v75, s[24:25]
	v_cndmask_b32_e64 v67, v212, v76, s[26:27]
	v_cndmask_b32_e64 v66, v212, v77, s[28:29]
	v_cndmask_b32_e64 v65, v212, v78, s[30:31]
	v_cndmask_b32_e64 v64, v212, v79, s[34:35]
	s_branch .LBB0_347
